# v14 with cost-weighted VALU spacing in the fused attention blocks (each MFMA leads an equal share of VALU cost, transcendental weighted 5/3)
# baseline (speedup 1.0000x reference)
.LBB0_742:
	s_add_i32 s27, s63, -3
	s_add_u32 s24, s76, s18
	s_addc_u32 s28, s77, s19
	s_add_u32 s10, s24, 0xe212000
	s_addc_u32 s11, s28, 0
	s_mul_i32 s25, s16, 0x6000
	v_lshl_add_u64 v[200:201], v[180:181], 1, s[10:11]
	s_add_i32 s12, s25, s49
	s_mov_b32 s13, m0
	s_mov_b32 m0, s12
	s_nop 0
	global_load_lds_dwordx4 v[200:201], off
	s_mov_b32 m0, s13
	v_lshl_add_u64 v[200:201], v[182:183], 1, s[10:11]
	s_mov_b32 s26, s16
	s_add_i32 s13, s12, 0x2000
	s_mov_b32 s16, m0
	s_mov_b32 m0, s13
	s_nop 0
	global_load_lds_dwordx4 v[200:201], off
	s_mov_b32 m0, s16
	v_lshl_add_u64 v[200:201], v[184:185], 1, s[10:11]
	s_add_i32 s10, s12, 0x4000
	s_add_u32 s29, s76, s20
	s_addc_u32 s30, s77, s21
	s_mov_b32 s11, m0
	s_mov_b32 m0, s10
	s_nop 0
	global_load_lds_dwordx4 v[200:201], off
	s_mov_b32 m0, s11
	s_add_u32 s10, s29, 0x14208000
	s_addc_u32 s11, s30, 0
	s_lshl_b32 s22, s4, 14
	s_add_i32 s12, s22, s51
	v_lshl_add_u64 v[200:201], v[186:187], 1, s[10:11]
	s_mov_b32 s13, m0
	s_mov_b32 m0, s12
	s_nop 0
	global_load_lds_dwordx4 v[200:201], off
	s_mov_b32 m0, s13
	v_lshl_add_u64 v[200:201], v[188:189], 1, s[10:11]
	s_add_i32 s10, s12, 0x2000
	s_mov_b32 s11, m0
	s_mov_b32 m0, s10
	s_nop 0
	global_load_lds_dwordx4 v[200:201], off
	s_mov_b32 m0, s11
	s_cmp_le_i32 s27, s52
	s_cselect_b64 s[12:13], -1, 0
	s_and_b64 vcc, exec, s[12:13]
	s_mul_i32 s31, s62, 0x6000
	s_cbranch_vccz .LBB0_745
	v_add_u32_e32 v232, s31, v206
	ds_read_b128 v[64:67], v232 offset:0
	ds_read_b128 v[68:71], v232 offset:12288
	v_add_u32_e32 v233, s31, v207
	ds_read_b128 v[200:203], v233 offset:0
	ds_read_b128 v[212:215], v233 offset:12288
	v_add_u32_e32 v234, s31, v208
	ds_read_b128 v[216:219], v234 offset:0
	ds_read_b128 v[220:223], v234 offset:12288
	s_waitcnt lgkmcnt(4)
	v_add_u32_e32 v235, s31, v209
	v_mfma_f32_32x32x16_bf16 v[80:95], v[64:67], v[172:175], 0
	v_add_f32_e32 v241, 0, v112
	v_add_f32_e32 v241, v113, v241
	v_add_f32_e32 v241, v114, v241
	v_add_f32_e32 v241, v115, v241
	ds_read_b128 v[224:227], v235 offset:0
	ds_read_b128 v[228:231], v235 offset:12288
	s_waitcnt lgkmcnt(4)
	v_mfma_f32_32x32x16_bf16 v[64:79], v[68:71], v[172:175], 0
	v_add_f32_e32 v241, v116, v241
	v_add_f32_e32 v241, v117, v241
	v_add_f32_e32 v241, v118, v241
	v_mfma_f32_32x32x16_bf16 v[80:95], v[200:203], v[168:171], v[80:95]
	v_add_f32_e32 v241, v119, v241
	v_add_f32_e32 v241, v120, v241
	v_add_f32_e32 v241, v121, v241
	v_add_f32_e32 v241, v122, v241
	ds_read_b128 v[200:203], v232 offset:128
	v_mfma_f32_32x32x16_bf16 v[64:79], v[212:215], v[168:171], v[64:79]
	v_add_f32_e32 v241, v123, v241
	v_exp_f32_e32 v96, v96
	v_add_f32_e32 v241, v124, v241
	ds_read_b128 v[212:215], v232 offset:12416
	s_waitcnt lgkmcnt(4)
	v_mfma_f32_32x32x16_bf16 v[80:95], v[216:219], v[164:167], v[80:95]
	v_exp_f32_e32 v97, v97
	v_add_f32_e32 v241, v125, v241
	v_exp_f32_e32 v98, v98
	ds_read_b128 v[216:219], v233 offset:128
	v_mfma_f32_32x32x16_bf16 v[64:79], v[220:223], v[164:167], v[64:79]
	v_add_f32_e32 v241, v126, v241
	v_exp_f32_e32 v99, v99
	ds_read_b128 v[220:223], v233 offset:12416
	s_waitcnt lgkmcnt(4)
	v_mfma_f32_32x32x16_bf16 v[80:95], v[224:227], v[160:163], v[80:95]
	v_add_f32_e32 v241, v127, v241
	v_exp_f32_e32 v100, v100
	v_add_f32_e32 v241, v96, v241
	ds_read_b128 v[224:227], v234 offset:128
	v_mfma_f32_32x32x16_bf16 v[64:79], v[228:231], v[160:163], v[64:79]
	v_exp_f32_e32 v101, v101
	v_add_f32_e32 v241, v97, v241
	v_exp_f32_e32 v102, v102
	ds_read_b128 v[228:231], v234 offset:12416
	s_waitcnt lgkmcnt(4)
	v_mfma_f32_32x32x16_bf16 v[80:95], v[200:203], v[156:159], v[80:95]
	v_add_f32_e32 v241, v98, v241
	v_exp_f32_e32 v103, v103
	v_add_f32_e32 v241, v99, v241
	ds_read_b128 v[200:203], v235 offset:128
	v_mfma_f32_32x32x16_bf16 v[64:79], v[212:215], v[156:159], v[64:79]
	v_exp_f32_e32 v104, v104
	v_add_f32_e32 v241, v100, v241
	ds_read_b128 v[212:215], v235 offset:12416
	s_waitcnt lgkmcnt(4)
	v_mfma_f32_32x32x16_bf16 v[80:95], v[216:219], v[152:155], v[80:95]
	v_exp_f32_e32 v105, v105
	v_add_f32_e32 v241, v101, v241
	v_exp_f32_e32 v106, v106
	ds_read_b128 v[216:219], v232 offset:256
	v_mfma_f32_32x32x16_bf16 v[64:79], v[220:223], v[152:155], v[64:79]
	v_add_f32_e32 v241, v102, v241
	v_exp_f32_e32 v107, v107
	v_add_f32_e32 v241, v103, v241
	ds_read_b128 v[220:223], v232 offset:12544
	s_waitcnt lgkmcnt(4)
	v_mfma_f32_32x32x16_bf16 v[80:95], v[224:227], v[148:151], v[80:95]
	v_exp_f32_e32 v108, v108
	v_add_f32_e32 v241, v104, v241
	ds_read_b128 v[224:227], v233 offset:256
	v_mfma_f32_32x32x16_bf16 v[64:79], v[228:231], v[148:151], v[64:79]
	v_exp_f32_e32 v109, v109
	v_add_f32_e32 v241, v105, v241
	v_exp_f32_e32 v110, v110
	ds_read_b128 v[228:231], v233 offset:12544
	s_waitcnt lgkmcnt(4)
	v_mfma_f32_32x32x16_bf16 v[80:95], v[200:203], v[144:147], v[80:95]
	v_add_f32_e32 v241, v106, v241
	v_exp_f32_e32 v111, v111
	v_add_f32_e32 v241, v107, v241
	ds_read_b128 v[200:203], v234 offset:256
	v_mfma_f32_32x32x16_bf16 v[64:79], v[212:215], v[144:147], v[64:79]
	v_add_f32_e32 v241, v108, v241
	v_add_f32_e32 v241, v109, v241
	v_add_f32_e32 v241, v110, v241
	v_add_f32_e32 v241, v111, v241
	ds_read_b128 v[212:215], v234 offset:12544
	s_waitcnt lgkmcnt(4)
	v_mfma_f32_32x32x16_bf16 v[80:95], v[216:219], v[140:143], v[80:95]
	v_mov_b32_e32 v242, v241
	v_cvt_pk_bf16_f32 v112, v112, v113
	v_cvt_pk_bf16_f32 v113, v114, v115
	ds_read_b128 v[216:219], v235 offset:256
	v_mfma_f32_32x32x16_bf16 v[64:79], v[220:223], v[140:143], v[64:79]
	v_permlane32_swap_b32_e32 v241, v242
	v_cvt_pk_bf16_f32 v114, v116, v117
	v_cvt_pk_bf16_f32 v115, v118, v119
	v_cvt_pk_bf16_f32 v116, v120, v121
	ds_read_b128 v[220:223], v235 offset:12544
	s_waitcnt lgkmcnt(4)
	v_mfma_f32_32x32x16_bf16 v[80:95], v[224:227], v[136:139], v[80:95]
	v_cvt_pk_bf16_f32 v117, v122, v123
	v_cvt_pk_bf16_f32 v118, v124, v125
	v_cvt_pk_bf16_f32 v119, v126, v127
	v_cvt_pk_bf16_f32 v96, v96, v97
	v_mfma_f32_32x32x16_bf16 v[64:79], v[228:231], v[136:139], v[64:79]
	v_cvt_pk_bf16_f32 v97, v98, v99
	v_cvt_pk_bf16_f32 v98, v100, v101
	v_cvt_pk_bf16_f32 v99, v102, v103
	s_waitcnt lgkmcnt(2)
	v_mfma_f32_32x32x16_bf16 v[80:95], v[200:203], v[132:135], v[80:95]
	v_cvt_pk_bf16_f32 v100, v104, v105
	v_cvt_pk_bf16_f32 v101, v106, v107
	v_cvt_pk_bf16_f32 v102, v108, v109
	v_cvt_pk_bf16_f32 v103, v110, v111
	v_mfma_f32_32x32x16_bf16 v[64:79], v[212:215], v[132:135], v[64:79]
	v_add_f32_e32 v243, v241, v242
	v_fmac_f32_e32 v243, v210, v211
	v_permlane32_swap_b32_e32 v112, v114
	v_permlane32_swap_b32_e32 v113, v115
	s_waitcnt lgkmcnt(0)
	v_mfma_f32_32x32x16_bf16 v[80:95], v[216:219], v[128:131], v[80:95]
	v_permlane32_swap_b32_e32 v116, v118
	v_permlane32_swap_b32_e32 v117, v119
	v_permlane32_swap_b32_e32 v96, v98
	v_mfma_f32_32x32x16_bf16 v[64:79], v[220:223], v[128:131], v[64:79]
	v_permlane32_swap_b32_e32 v97, v99
	v_permlane32_swap_b32_e32 v100, v102
	v_permlane32_swap_b32_e32 v101, v103
	v_mov_b32_e32 v211, v243
	v_lshl_add_u32 v244, s26, 14, v196
	ds_read_b64_tr_b16 v[224:225], v244 offset:0
	ds_read_b64_tr_b16 v[226:227], v244 offset:2048
	ds_read_b64_tr_b16 v[228:229], v244 offset:512
	ds_read_b64_tr_b16 v[230:231], v244 offset:2560
	ds_read_b64_tr_b16 v[232:233], v244 offset:1024
	ds_read_b64_tr_b16 v[234:235], v244 offset:3072
	ds_read_b64_tr_b16 v[236:237], v244 offset:1536
	ds_read_b64_tr_b16 v[238:239], v244 offset:3584
	s_waitcnt lgkmcnt(0)
	v_mfma_f32_32x32x16_bf16 v[32:47], v[112:115], v[224:227], v[32:47]
	v_max_f32_e32 v246, v81, v81
	v_max_f32_e32 v247, v80, v80
	v_max_f32_e32 v246, v247, v246
	v_max3_f32 v246, v246, v82, v83
	v_max3_f32 v246, v246, v84, v85
	ds_read_b64_tr_b16 v[200:201], v244 offset:4096
	ds_read_b64_tr_b16 v[202:203], v244 offset:6144
	ds_read_b64_tr_b16 v[212:213], v244 offset:4608
	ds_read_b64_tr_b16 v[214:215], v244 offset:6656
	ds_read_b64_tr_b16 v[216:217], v244 offset:5120
	ds_read_b64_tr_b16 v[218:219], v244 offset:7168
	ds_read_b64_tr_b16 v[220:221], v244 offset:5632
	ds_read_b64_tr_b16 v[222:223], v244 offset:7680
	v_mfma_f32_32x32x16_bf16 v[48:63], v[112:115], v[228:231], v[48:63]
	v_max3_f32 v246, v246, v86, v87
	v_max3_f32 v246, v246, v88, v89
	v_max3_f32 v246, v246, v90, v91
	v_max3_f32 v246, v246, v92, v93
	v_max3_f32 v246, v246, v94, v95
	v_max3_f32 v246, v246, v64, v65
	v_mfma_f32_32x32x16_bf16 v[0:15], v[112:115], v[232:235], v[0:15]
	v_max3_f32 v246, v246, v66, v67
	v_max3_f32 v246, v246, v68, v69
	v_max3_f32 v246, v246, v70, v71
	v_max3_f32 v246, v246, v72, v73
	v_max3_f32 v246, v246, v74, v75
	v_mfma_f32_32x32x16_bf16 v[16:31], v[112:115], v[236:239], v[16:31]
	v_max3_f32 v246, v246, v76, v77
	v_max3_f32 v246, v246, v78, v79
	v_mov_b32_e32 v247, v246
	s_nop 1
	v_permlane32_swap_b32_e32 v246, v247
	v_max_f32_e32 v247, v247, v247
	s_waitcnt lgkmcnt(0)
	v_mfma_f32_32x32x16_bf16 v[32:47], v[116:119], v[200:203], v[32:47]
	v_max_f32_e32 v246, v246, v246
	v_max_f32_e32 v246, v246, v247
	v_sub_f32_e32 v247, v246, v204
	v_cmp_ge_f32_e32 vcc, s0, v247
	v_max_f32_e32 v247, v204, v204
	v_max_f32_e32 v248, v247, v246
	ds_read_b64_tr_b16 v[224:225], v244 offset:8192
	ds_read_b64_tr_b16 v[226:227], v244 offset:10240
	ds_read_b64_tr_b16 v[228:229], v244 offset:8704
	ds_read_b64_tr_b16 v[230:231], v244 offset:10752
	ds_read_b64_tr_b16 v[232:233], v244 offset:9216
	ds_read_b64_tr_b16 v[234:235], v244 offset:11264
	ds_read_b64_tr_b16 v[236:237], v244 offset:9728
	ds_read_b64_tr_b16 v[238:239], v244 offset:11776
	v_mfma_f32_32x32x16_bf16 v[48:63], v[116:119], v[212:215], v[48:63]
	v_sub_f32_e32 v246, v204, v248
	v_mul_f32_e32 v246, 0x3dd53b94, v246
	v_exp_f32_e32 v246, v246
	s_cmp_eq_u64 vcc, exec
	s_cselect_b64 s[12:13], -1, 0
	v_cndmask_b32_e64 v205, v246, 1.0, s[12:13]
	v_mfma_f32_32x32x16_bf16 v[0:15], v[116:119], v[216:219], v[0:15]
	v_cndmask_b32_e64 v204, v248, v204, s[12:13]
	v_mul_f32_e32 v246, 0xbdd53b94, v204
	v_mov_b32_e32 v247, v246
	v_fmamk_f32 v80, v80, 0x3dd53b94, v246
	v_fmamk_f32 v81, v81, 0x3dd53b94, v246
	v_fmamk_f32 v82, v82, 0x3dd53b94, v246
	v_mfma_f32_32x32x16_bf16 v[16:31], v[116:119], v[220:223], v[16:31]
	v_fmamk_f32 v83, v83, 0x3dd53b94, v246
	v_fmamk_f32 v84, v84, 0x3dd53b94, v246
	v_fmamk_f32 v85, v85, 0x3dd53b94, v246
	v_fmamk_f32 v86, v86, 0x3dd53b94, v246
	v_fmamk_f32 v87, v87, 0x3dd53b94, v246
	s_waitcnt lgkmcnt(0)
	v_mfma_f32_32x32x16_bf16 v[32:47], v[96:99], v[224:227], v[32:47]
	v_fmamk_f32 v88, v88, 0x3dd53b94, v246
	v_fmamk_f32 v89, v89, 0x3dd53b94, v246
	v_fmamk_f32 v90, v90, 0x3dd53b94, v246
	v_fmamk_f32 v91, v91, 0x3dd53b94, v246
	v_fmamk_f32 v92, v92, 0x3dd53b94, v246
	ds_read_b64_tr_b16 v[200:201], v244 offset:12288
	ds_read_b64_tr_b16 v[202:203], v244 offset:14336
	ds_read_b64_tr_b16 v[212:213], v244 offset:12800
	ds_read_b64_tr_b16 v[214:215], v244 offset:14848
	ds_read_b64_tr_b16 v[216:217], v244 offset:13312
	ds_read_b64_tr_b16 v[218:219], v244 offset:15360
	ds_read_b64_tr_b16 v[220:221], v244 offset:13824
	ds_read_b64_tr_b16 v[222:223], v244 offset:15872
	v_mfma_f32_32x32x16_bf16 v[48:63], v[96:99], v[228:231], v[48:63]
	v_fmamk_f32 v93, v93, 0x3dd53b94, v246
	v_fmamk_f32 v94, v94, 0x3dd53b94, v246
	v_fmac_f32_e32 v247, 0x3dd53b94, v95
	v_exp_f32_e32 v80, v80
	v_exp_f32_e32 v81, v81
	v_mfma_f32_32x32x16_bf16 v[0:15], v[96:99], v[232:235], v[0:15]
	v_exp_f32_e32 v82, v82
	v_exp_f32_e32 v83, v83
	v_exp_f32_e32 v84, v84
	v_mfma_f32_32x32x16_bf16 v[16:31], v[96:99], v[236:239], v[16:31]
	v_exp_f32_e32 v85, v85
	v_exp_f32_e32 v86, v86
	v_exp_f32_e32 v87, v87
	s_waitcnt lgkmcnt(0)
	v_mfma_f32_32x32x16_bf16 v[32:47], v[100:103], v[200:203], v[32:47]
	v_exp_f32_e32 v88, v88
	v_exp_f32_e32 v89, v89
	v_exp_f32_e32 v90, v90
	v_mfma_f32_32x32x16_bf16 v[48:63], v[100:103], v[212:215], v[48:63]
	v_exp_f32_e32 v91, v91
	v_exp_f32_e32 v92, v92
	v_exp_f32_e32 v93, v93
	v_mfma_f32_32x32x16_bf16 v[0:15], v[100:103], v[216:219], v[0:15]
	v_exp_f32_e32 v94, v94
	v_exp_f32_e32 v95, v247
	v_pk_fma_f32 v[78:79], v[78:79], s[68:69], v[246:247] op_sel_hi:[1,0,0]
	v_pk_fma_f32 v[76:77], v[76:77], s[68:69], v[246:247] op_sel_hi:[1,0,0]
	v_pk_fma_f32 v[74:75], v[74:75], s[68:69], v[246:247] op_sel_hi:[1,0,0]
	v_mfma_f32_32x32x16_bf16 v[16:31], v[100:103], v[220:223], v[16:31]
	v_pk_fma_f32 v[72:73], v[72:73], s[68:69], v[246:247] op_sel_hi:[1,0,0]
	v_pk_fma_f32 v[70:71], v[70:71], s[68:69], v[246:247] op_sel_hi:[1,0,0]
	v_pk_fma_f32 v[68:69], v[68:69], s[68:69], v[246:247] op_sel_hi:[1,0,0]
	v_pk_fma_f32 v[66:67], v[66:67], s[68:69], v[246:247] op_sel_hi:[1,0,0]
	v_pk_fma_f32 v[64:65], v[64:65], s[68:69], v[246:247] op_sel_hi:[1,0,0]
	s_mov_b64 s[10:11], 0
	v_cmp_gt_f32_e32 vcc, 1.0, v205
	s_cbranch_vccz .LBB0_752
	s_nop 7
	s_nop 4
	s_and_saveexec_b64 s[16:17], s[8:9]
	ds_write_b32 v195, v205 offset:128
	s_or_b64 exec, exec, s[16:17]
	s_waitcnt lgkmcnt(0)
	v_add_u32_e32 v213, s48, v176
	ds_read_b128 v[200:203], v213 offset:224
	ds_read_b128 v[214:217], v213 offset:192
	ds_read_b128 v[218:221], v213 offset:160
	ds_read_b128 v[222:225], v213 offset:128
	s_waitcnt lgkmcnt(3)
	v_pk_mul_f32 v[44:45], v[44:45], v[200:201]
	s_waitcnt lgkmcnt(2)
	v_pk_mul_f32 v[40:41], v[40:41], v[214:215]
	s_waitcnt lgkmcnt(1)
	v_pk_mul_f32 v[36:37], v[36:37], v[218:219]
	v_pk_mul_f32 v[46:47], v[46:47], v[202:203]
	v_pk_mul_f32 v[42:43], v[42:43], v[216:217]
	v_pk_mul_f32 v[38:39], v[38:39], v[220:221]
	s_waitcnt lgkmcnt(0)
	v_pk_mul_f32 v[34:35], v[34:35], v[224:225]
	v_pk_mul_f32 v[32:33], v[32:33], v[222:223]
	v_pk_mul_f32 v[60:61], v[60:61], v[200:201]
	v_pk_mul_f32 v[56:57], v[56:57], v[214:215]
	v_pk_mul_f32 v[52:53], v[52:53], v[218:219]
	v_pk_mul_f32 v[62:63], v[62:63], v[202:203]
	v_pk_mul_f32 v[58:59], v[58:59], v[216:217]
	v_pk_mul_f32 v[54:55], v[54:55], v[220:221]
	v_pk_mul_f32 v[50:51], v[50:51], v[224:225]
	v_pk_mul_f32 v[48:49], v[48:49], v[222:223]
	v_pk_mul_f32 v[12:13], v[12:13], v[200:201]
	v_pk_mul_f32 v[8:9], v[8:9], v[214:215]
	v_pk_mul_f32 v[4:5], v[4:5], v[218:219]
	v_pk_mul_f32 v[14:15], v[14:15], v[202:203]
	v_pk_mul_f32 v[10:11], v[10:11], v[216:217]
	v_pk_mul_f32 v[6:7], v[6:7], v[220:221]
	v_pk_mul_f32 v[2:3], v[2:3], v[224:225]
	v_pk_mul_f32 v[0:1], v[0:1], v[222:223]
	v_pk_mul_f32 v[28:29], v[28:29], v[200:201]
	v_pk_mul_f32 v[24:25], v[24:25], v[214:215]
	v_pk_mul_f32 v[20:21], v[20:21], v[218:219]
	v_pk_mul_f32 v[30:31], v[30:31], v[202:203]
	v_pk_mul_f32 v[26:27], v[26:27], v[216:217]
	v_pk_mul_f32 v[22:23], v[22:23], v[220:221]
	v_pk_mul_f32 v[18:19], v[18:19], v[224:225]
	v_pk_mul_f32 v[16:17], v[16:17], v[222:223]
	s_branch .LBB0_752

.LBB0_754:
	s_add_u32 s16, s29, 0x1420c000
	s_addc_u32 s17, s30, 0
	s_lshl_b32 s24, s26, 14
	s_add_i32 s28, s24, s51
	v_lshl_add_u64 v[200:201], v[186:187], 1, s[16:17]
	s_mov_b32 s29, m0
	s_mov_b32 m0, s28
	s_nop 0
	global_load_lds_dwordx4 v[200:201], off
	s_mov_b32 m0, s29
	s_addk_i32 s28, 0x2000
	s_cmp_lt_i32 s27, s52
	v_lshl_add_u64 v[200:201], v[188:189], 1, s[16:17]
	s_cselect_b64 s[16:17], -1, 0
	s_cmp_ge_i32 s27, s52
	s_mov_b32 s27, m0
	s_mov_b32 m0, s28
	s_nop 0
	global_load_lds_dwordx4 v[200:201], off
	s_mov_b32 m0, s27
	s_cbranch_scc1 .LBB0_766
	s_mul_i32 s27, s4, 0x6000
	v_add_u32_e32 v232, s27, v206
	ds_read_b128 v[96:99], v232 offset:0
	ds_read_b128 v[100:103], v232 offset:12288
	v_add_u32_e32 v233, s27, v207
	ds_read_b128 v[200:203], v233 offset:0
	ds_read_b128 v[212:215], v233 offset:12288
	v_add_u32_e32 v234, s27, v208
	ds_read_b128 v[216:219], v234 offset:0
	ds_read_b128 v[220:223], v234 offset:12288
	s_waitcnt lgkmcnt(4)
	v_add_u32_e32 v235, s27, v209
	v_mfma_f32_32x32x16_bf16 v[112:127], v[96:99], v[172:175], 0
	v_add_f32_e32 v241, 0, v80
	v_add_f32_e32 v241, v81, v241
	v_add_f32_e32 v241, v82, v241
	v_add_f32_e32 v241, v83, v241
	ds_read_b128 v[224:227], v235 offset:0
	ds_read_b128 v[228:231], v235 offset:12288
	s_waitcnt lgkmcnt(4)
	v_mfma_f32_32x32x16_bf16 v[96:111], v[100:103], v[172:175], 0
	v_add_f32_e32 v241, v84, v241
	v_add_f32_e32 v241, v85, v241
	v_add_f32_e32 v241, v86, v241
	v_mfma_f32_32x32x16_bf16 v[112:127], v[200:203], v[168:171], v[112:127]
	v_add_f32_e32 v241, v87, v241
	v_add_f32_e32 v241, v88, v241
	v_add_f32_e32 v241, v89, v241
	v_add_f32_e32 v241, v90, v241
	ds_read_b128 v[200:203], v232 offset:128
	v_mfma_f32_32x32x16_bf16 v[96:111], v[212:215], v[168:171], v[96:111]
	v_add_f32_e32 v241, v91, v241
	v_exp_f32_e32 v64, v64
	v_add_f32_e32 v241, v92, v241
	ds_read_b128 v[212:215], v232 offset:12416
	s_waitcnt lgkmcnt(4)
	v_mfma_f32_32x32x16_bf16 v[112:127], v[216:219], v[164:167], v[112:127]
	v_exp_f32_e32 v65, v65
	v_add_f32_e32 v241, v93, v241
	v_exp_f32_e32 v66, v66
	ds_read_b128 v[216:219], v233 offset:128
	v_mfma_f32_32x32x16_bf16 v[96:111], v[220:223], v[164:167], v[96:111]
	v_add_f32_e32 v241, v94, v241
	v_exp_f32_e32 v67, v67
	ds_read_b128 v[220:223], v233 offset:12416
	s_waitcnt lgkmcnt(4)
	v_mfma_f32_32x32x16_bf16 v[112:127], v[224:227], v[160:163], v[112:127]
	v_add_f32_e32 v241, v95, v241
	v_exp_f32_e32 v68, v68
	v_add_f32_e32 v241, v64, v241
	ds_read_b128 v[224:227], v234 offset:128
	v_mfma_f32_32x32x16_bf16 v[96:111], v[228:231], v[160:163], v[96:111]
	v_exp_f32_e32 v69, v69
	v_add_f32_e32 v241, v65, v241
	v_exp_f32_e32 v70, v70
	ds_read_b128 v[228:231], v234 offset:12416
	s_waitcnt lgkmcnt(4)
	v_mfma_f32_32x32x16_bf16 v[112:127], v[200:203], v[156:159], v[112:127]
	v_add_f32_e32 v241, v66, v241
	v_exp_f32_e32 v71, v71
	v_add_f32_e32 v241, v67, v241
	ds_read_b128 v[200:203], v235 offset:128
	v_mfma_f32_32x32x16_bf16 v[96:111], v[212:215], v[156:159], v[96:111]
	v_exp_f32_e32 v72, v72
	v_add_f32_e32 v241, v68, v241
	ds_read_b128 v[212:215], v235 offset:12416
	s_waitcnt lgkmcnt(4)
	v_mfma_f32_32x32x16_bf16 v[112:127], v[216:219], v[152:155], v[112:127]
	v_exp_f32_e32 v73, v73
	v_add_f32_e32 v241, v69, v241
	v_exp_f32_e32 v74, v74
	ds_read_b128 v[216:219], v232 offset:256
	v_mfma_f32_32x32x16_bf16 v[96:111], v[220:223], v[152:155], v[96:111]
	v_add_f32_e32 v241, v70, v241
	v_exp_f32_e32 v75, v75
	v_add_f32_e32 v241, v71, v241
	ds_read_b128 v[220:223], v232 offset:12544
	s_waitcnt lgkmcnt(4)
	v_mfma_f32_32x32x16_bf16 v[112:127], v[224:227], v[148:151], v[112:127]
	v_exp_f32_e32 v76, v76
	v_add_f32_e32 v241, v72, v241
	ds_read_b128 v[224:227], v233 offset:256
	v_mfma_f32_32x32x16_bf16 v[96:111], v[228:231], v[148:151], v[96:111]
	v_exp_f32_e32 v77, v77
	v_add_f32_e32 v241, v73, v241
	v_exp_f32_e32 v78, v78
	ds_read_b128 v[228:231], v233 offset:12544
	s_waitcnt lgkmcnt(4)
	v_mfma_f32_32x32x16_bf16 v[112:127], v[200:203], v[144:147], v[112:127]
	v_add_f32_e32 v241, v74, v241
	v_exp_f32_e32 v79, v79
	v_add_f32_e32 v241, v75, v241
	ds_read_b128 v[200:203], v234 offset:256
	v_mfma_f32_32x32x16_bf16 v[96:111], v[212:215], v[144:147], v[96:111]
	v_add_f32_e32 v241, v76, v241
	v_add_f32_e32 v241, v77, v241
	v_add_f32_e32 v241, v78, v241
	v_add_f32_e32 v241, v79, v241
	ds_read_b128 v[212:215], v234 offset:12544
	s_waitcnt lgkmcnt(4)
	v_mfma_f32_32x32x16_bf16 v[112:127], v[216:219], v[140:143], v[112:127]
	v_mov_b32_e32 v242, v241
	v_cvt_pk_bf16_f32 v80, v80, v81
	v_cvt_pk_bf16_f32 v81, v82, v83
	ds_read_b128 v[216:219], v235 offset:256
	v_mfma_f32_32x32x16_bf16 v[96:111], v[220:223], v[140:143], v[96:111]
	v_permlane32_swap_b32_e32 v241, v242
	v_cvt_pk_bf16_f32 v82, v84, v85
	v_cvt_pk_bf16_f32 v83, v86, v87
	v_cvt_pk_bf16_f32 v84, v88, v89
	ds_read_b128 v[220:223], v235 offset:12544
	s_waitcnt lgkmcnt(4)
	v_mfma_f32_32x32x16_bf16 v[112:127], v[224:227], v[136:139], v[112:127]
	v_cvt_pk_bf16_f32 v85, v90, v91
	v_cvt_pk_bf16_f32 v86, v92, v93
	v_cvt_pk_bf16_f32 v87, v94, v95
	v_cvt_pk_bf16_f32 v64, v64, v65
	v_mfma_f32_32x32x16_bf16 v[96:111], v[228:231], v[136:139], v[96:111]
	v_cvt_pk_bf16_f32 v65, v66, v67
	v_cvt_pk_bf16_f32 v66, v68, v69
	v_cvt_pk_bf16_f32 v67, v70, v71
	s_waitcnt lgkmcnt(2)
	v_mfma_f32_32x32x16_bf16 v[112:127], v[200:203], v[132:135], v[112:127]
	v_cvt_pk_bf16_f32 v68, v72, v73
	v_cvt_pk_bf16_f32 v69, v74, v75
	v_cvt_pk_bf16_f32 v70, v76, v77
	v_cvt_pk_bf16_f32 v71, v78, v79
	v_mfma_f32_32x32x16_bf16 v[96:111], v[212:215], v[132:135], v[96:111]
	v_add_f32_e32 v243, v241, v242
	v_fmac_f32_e32 v243, v205, v211
	v_permlane32_swap_b32_e32 v80, v82
	v_permlane32_swap_b32_e32 v81, v83
	s_waitcnt lgkmcnt(0)
	v_mfma_f32_32x32x16_bf16 v[112:127], v[216:219], v[128:131], v[112:127]
	v_permlane32_swap_b32_e32 v84, v86
	v_permlane32_swap_b32_e32 v85, v87
	v_permlane32_swap_b32_e32 v64, v66
	v_mfma_f32_32x32x16_bf16 v[96:111], v[220:223], v[128:131], v[96:111]
	v_permlane32_swap_b32_e32 v65, v67
	v_permlane32_swap_b32_e32 v68, v70
	v_permlane32_swap_b32_e32 v69, v71
	v_mov_b32_e32 v211, v243
	v_lshl_add_u32 v244, s62, 14, v196
	ds_read_b64_tr_b16 v[224:225], v244 offset:0
	ds_read_b64_tr_b16 v[226:227], v244 offset:2048
	ds_read_b64_tr_b16 v[228:229], v244 offset:512
	ds_read_b64_tr_b16 v[230:231], v244 offset:2560
	ds_read_b64_tr_b16 v[232:233], v244 offset:1024
	ds_read_b64_tr_b16 v[234:235], v244 offset:3072
	ds_read_b64_tr_b16 v[236:237], v244 offset:1536
	ds_read_b64_tr_b16 v[238:239], v244 offset:3584
	s_waitcnt lgkmcnt(0)
	v_mfma_f32_32x32x16_bf16 v[32:47], v[80:83], v[224:227], v[32:47]
	v_max_f32_e32 v246, v113, v113
	v_max_f32_e32 v247, v112, v112
	v_max_f32_e32 v246, v247, v246
	v_max3_f32 v246, v246, v114, v115
	v_max3_f32 v246, v246, v116, v117
	ds_read_b64_tr_b16 v[200:201], v244 offset:4096
	ds_read_b64_tr_b16 v[202:203], v244 offset:6144
	ds_read_b64_tr_b16 v[212:213], v244 offset:4608
	ds_read_b64_tr_b16 v[214:215], v244 offset:6656
	ds_read_b64_tr_b16 v[216:217], v244 offset:5120
	ds_read_b64_tr_b16 v[218:219], v244 offset:7168
	ds_read_b64_tr_b16 v[220:221], v244 offset:5632
	ds_read_b64_tr_b16 v[222:223], v244 offset:7680
	v_mfma_f32_32x32x16_bf16 v[48:63], v[80:83], v[228:231], v[48:63]
	v_max3_f32 v246, v246, v118, v119
	v_max3_f32 v246, v246, v120, v121
	v_max3_f32 v246, v246, v122, v123
	v_max3_f32 v246, v246, v124, v125
	v_max3_f32 v246, v246, v126, v127
	v_max3_f32 v246, v246, v96, v97
	v_mfma_f32_32x32x16_bf16 v[0:15], v[80:83], v[232:235], v[0:15]
	v_max3_f32 v246, v246, v98, v99
	v_max3_f32 v246, v246, v100, v101
	v_max3_f32 v246, v246, v102, v103
	v_max3_f32 v246, v246, v104, v105
	v_max3_f32 v246, v246, v106, v107
	v_mfma_f32_32x32x16_bf16 v[16:31], v[80:83], v[236:239], v[16:31]
	v_max3_f32 v246, v246, v108, v109
	v_max3_f32 v246, v246, v110, v111
	v_mov_b32_e32 v247, v246
	s_nop 1
	v_permlane32_swap_b32_e32 v246, v247
	v_max_f32_e32 v247, v247, v247
	s_waitcnt lgkmcnt(0)
	v_mfma_f32_32x32x16_bf16 v[32:47], v[84:87], v[200:203], v[32:47]
	v_max_f32_e32 v246, v246, v246
	v_max_f32_e32 v246, v246, v247
	v_sub_f32_e32 v247, v246, v204
	v_cmp_ge_f32_e32 vcc, s0, v247
	v_max_f32_e32 v247, v204, v204
	v_max_f32_e32 v248, v247, v246
	ds_read_b64_tr_b16 v[224:225], v244 offset:8192
	ds_read_b64_tr_b16 v[226:227], v244 offset:10240
	ds_read_b64_tr_b16 v[228:229], v244 offset:8704
	ds_read_b64_tr_b16 v[230:231], v244 offset:10752
	ds_read_b64_tr_b16 v[232:233], v244 offset:9216
	ds_read_b64_tr_b16 v[234:235], v244 offset:11264
	ds_read_b64_tr_b16 v[236:237], v244 offset:9728
	ds_read_b64_tr_b16 v[238:239], v244 offset:11776
	v_mfma_f32_32x32x16_bf16 v[48:63], v[84:87], v[212:215], v[48:63]
	v_sub_f32_e32 v246, v204, v248
	v_mul_f32_e32 v246, 0x3dd53b94, v246
	v_exp_f32_e32 v246, v246
	s_cmp_eq_u64 vcc, exec
	s_cselect_b64 s[10:11], -1, 0
	v_cndmask_b32_e64 v210, v246, 1.0, s[10:11]
	v_mfma_f32_32x32x16_bf16 v[0:15], v[84:87], v[216:219], v[0:15]
	v_cndmask_b32_e64 v204, v248, v204, s[10:11]
	v_mul_f32_e32 v246, 0xbdd53b94, v204
	v_mov_b32_e32 v247, v246
	v_fmamk_f32 v112, v112, 0x3dd53b94, v246
	v_fmamk_f32 v113, v113, 0x3dd53b94, v246
	v_fmamk_f32 v114, v114, 0x3dd53b94, v246
	v_mfma_f32_32x32x16_bf16 v[16:31], v[84:87], v[220:223], v[16:31]
	v_fmamk_f32 v115, v115, 0x3dd53b94, v246
	v_fmamk_f32 v116, v116, 0x3dd53b94, v246
	v_fmamk_f32 v117, v117, 0x3dd53b94, v246
	v_fmamk_f32 v118, v118, 0x3dd53b94, v246
	v_fmamk_f32 v119, v119, 0x3dd53b94, v246
	s_waitcnt lgkmcnt(0)
	v_mfma_f32_32x32x16_bf16 v[32:47], v[64:67], v[224:227], v[32:47]
	v_fmamk_f32 v120, v120, 0x3dd53b94, v246
	v_fmamk_f32 v121, v121, 0x3dd53b94, v246
	v_fmamk_f32 v122, v122, 0x3dd53b94, v246
	v_fmamk_f32 v123, v123, 0x3dd53b94, v246
	v_fmamk_f32 v124, v124, 0x3dd53b94, v246
	ds_read_b64_tr_b16 v[200:201], v244 offset:12288
	ds_read_b64_tr_b16 v[202:203], v244 offset:14336
	ds_read_b64_tr_b16 v[212:213], v244 offset:12800
	ds_read_b64_tr_b16 v[214:215], v244 offset:14848
	ds_read_b64_tr_b16 v[216:217], v244 offset:13312
	ds_read_b64_tr_b16 v[218:219], v244 offset:15360
	ds_read_b64_tr_b16 v[220:221], v244 offset:13824
	ds_read_b64_tr_b16 v[222:223], v244 offset:15872
	v_mfma_f32_32x32x16_bf16 v[48:63], v[64:67], v[228:231], v[48:63]
	v_fmamk_f32 v125, v125, 0x3dd53b94, v246
	v_fmamk_f32 v126, v126, 0x3dd53b94, v246
	v_fmac_f32_e32 v247, 0x3dd53b94, v127
	v_exp_f32_e32 v112, v112
	v_exp_f32_e32 v113, v113
	v_mfma_f32_32x32x16_bf16 v[0:15], v[64:67], v[232:235], v[0:15]
	v_exp_f32_e32 v114, v114
	v_exp_f32_e32 v115, v115
	v_exp_f32_e32 v116, v116
	v_mfma_f32_32x32x16_bf16 v[16:31], v[64:67], v[236:239], v[16:31]
	v_exp_f32_e32 v117, v117
	v_exp_f32_e32 v118, v118
	v_exp_f32_e32 v119, v119
	s_waitcnt lgkmcnt(0)
	v_mfma_f32_32x32x16_bf16 v[32:47], v[68:71], v[200:203], v[32:47]
	v_exp_f32_e32 v120, v120
	v_exp_f32_e32 v121, v121
	v_exp_f32_e32 v122, v122
	v_mfma_f32_32x32x16_bf16 v[48:63], v[68:71], v[212:215], v[48:63]
	v_exp_f32_e32 v123, v123
	v_exp_f32_e32 v124, v124
	v_exp_f32_e32 v125, v125
	v_mfma_f32_32x32x16_bf16 v[0:15], v[68:71], v[216:219], v[0:15]
	v_exp_f32_e32 v126, v126
	v_exp_f32_e32 v127, v247
	v_pk_fma_f32 v[110:111], v[110:111], s[68:69], v[246:247] op_sel_hi:[1,0,0]
	v_pk_fma_f32 v[108:109], v[108:109], s[68:69], v[246:247] op_sel_hi:[1,0,0]
	v_pk_fma_f32 v[106:107], v[106:107], s[68:69], v[246:247] op_sel_hi:[1,0,0]
	v_mfma_f32_32x32x16_bf16 v[16:31], v[68:71], v[220:223], v[16:31]
	v_pk_fma_f32 v[104:105], v[104:105], s[68:69], v[246:247] op_sel_hi:[1,0,0]
	v_pk_fma_f32 v[102:103], v[102:103], s[68:69], v[246:247] op_sel_hi:[1,0,0]
	v_pk_fma_f32 v[100:101], v[100:101], s[68:69], v[246:247] op_sel_hi:[1,0,0]
	v_pk_fma_f32 v[98:99], v[98:99], s[68:69], v[246:247] op_sel_hi:[1,0,0]
	v_pk_fma_f32 v[96:97], v[96:97], s[68:69], v[246:247] op_sel_hi:[1,0,0]
	v_cmp_gt_f32_e32 vcc, 1.0, v210
	s_cbranch_vccz .Lh2_tail
	s_nop 7
	s_nop 4
	s_and_saveexec_b64 s[16:17], s[8:9]
	ds_write_b32 v195, v210 offset:128
	s_or_b64 exec, exec, s[16:17]
	s_waitcnt lgkmcnt(0)
	v_add_u32_e32 v213, s48, v176
	ds_read_b128 v[200:203], v213 offset:224
	ds_read_b128 v[214:217], v213 offset:192
	ds_read_b128 v[218:221], v213 offset:160
	ds_read_b128 v[222:225], v213 offset:128
	s_waitcnt lgkmcnt(3)
	v_pk_mul_f32 v[44:45], v[44:45], v[200:201]
	s_waitcnt lgkmcnt(2)
	v_pk_mul_f32 v[40:41], v[40:41], v[214:215]
	s_waitcnt lgkmcnt(1)
	v_pk_mul_f32 v[36:37], v[36:37], v[218:219]
	v_pk_mul_f32 v[46:47], v[46:47], v[202:203]
	v_pk_mul_f32 v[42:43], v[42:43], v[216:217]
	v_pk_mul_f32 v[38:39], v[38:39], v[220:221]
	s_waitcnt lgkmcnt(0)
	v_pk_mul_f32 v[34:35], v[34:35], v[224:225]
	v_pk_mul_f32 v[32:33], v[32:33], v[222:223]
	v_pk_mul_f32 v[60:61], v[60:61], v[200:201]
	v_pk_mul_f32 v[56:57], v[56:57], v[214:215]
	v_pk_mul_f32 v[52:53], v[52:53], v[218:219]
	v_pk_mul_f32 v[62:63], v[62:63], v[202:203]
	v_pk_mul_f32 v[58:59], v[58:59], v[216:217]
	v_pk_mul_f32 v[54:55], v[54:55], v[220:221]
	v_pk_mul_f32 v[50:51], v[50:51], v[224:225]
	v_pk_mul_f32 v[48:49], v[48:49], v[222:223]
	v_pk_mul_f32 v[12:13], v[12:13], v[200:201]
	v_pk_mul_f32 v[8:9], v[8:9], v[214:215]
	v_pk_mul_f32 v[4:5], v[4:5], v[218:219]
	v_pk_mul_f32 v[14:15], v[14:15], v[202:203]
	v_pk_mul_f32 v[10:11], v[10:11], v[216:217]
	v_pk_mul_f32 v[6:7], v[6:7], v[220:221]
	v_pk_mul_f32 v[2:3], v[2:3], v[224:225]
	v_pk_mul_f32 v[0:1], v[0:1], v[222:223]
	v_pk_mul_f32 v[28:29], v[28:29], v[200:201]
	v_pk_mul_f32 v[24:25], v[24:25], v[214:215]
	v_pk_mul_f32 v[20:21], v[20:21], v[218:219]
	v_pk_mul_f32 v[30:31], v[30:31], v[202:203]
	v_pk_mul_f32 v[26:27], v[26:27], v[216:217]
	v_pk_mul_f32 v[22:23], v[22:23], v[220:221]
	v_pk_mul_f32 v[18:19], v[18:19], v[224:225]
	v_pk_mul_f32 v[16:17], v[16:17], v[222:223]
	s_branch .Lh2_tail
